# attention fast path: MFMA-gap fillers in dataflow order (sub/exp interleaved) and spread by cost weight (exp = 5/3) instead of by count
# speedup vs baseline: 1.0049x; 1.0049x over previous
.LaF1_fast:
	s_waitcnt vmcnt(0)
	s_bitcmp1_b32 s51, 0
	s_cselect_b32 s53, 0, 0xac00
	s_setprio 1
	v_add_u32_e32 v253, s53, v171
	v_add_u32_e32 v252, s53, v181
	ds_read_b128 v[196:199], v253
	ds_read_b128 v[200:203], v253 offset:12800
	ds_read_b128 v[204:207], v253 offset:32
	ds_read_b128 v[208:211], v253 offset:12832
	ds_read_b128 v[212:215], v253 offset:64
	ds_read_b128 v[216:219], v253 offset:12864
	s_waitcnt lgkmcnt(5)
	v_mfma_f32_32x32x16_bf16 v[66:81], v[196:199], v[110:113], 0
	ds_read_b128 v[220:223], v253 offset:96
	s_waitcnt lgkmcnt(5)
	v_mfma_f32_32x32x16_bf16 v[82:97], v[200:203], v[110:113], 0
	ds_read_b128 v[224:227], v253 offset:12896
	v_lshl_add_u64 v[244:245], s[2:3], 0, v[176:177]
	s_waitcnt lgkmcnt(5)
	v_mfma_f32_32x32x16_bf16 v[66:81], v[204:207], v[118:121], v[66:81]
	ds_read_b128 v[228:231], v253 offset:128
	v_add_co_u32_e32 v246, vcc, 0x16020000, v244
	s_waitcnt lgkmcnt(5)
	v_mfma_f32_32x32x16_bf16 v[82:97], v[208:211], v[118:121], v[82:97]
	ds_read_b128 v[232:235], v253 offset:12928
	s_nop 1
	s_waitcnt lgkmcnt(5)
	v_mfma_f32_32x32x16_bf16 v[66:81], v[212:215], v[122:125], v[66:81]
	ds_read_b128 v[236:239], v253 offset:160
	v_addc_co_u32_e32 v247, vcc, 0, v245, vcc
	s_waitcnt lgkmcnt(5)
	v_mfma_f32_32x32x16_bf16 v[82:97], v[216:219], v[122:125], v[82:97]
	ds_read_b128 v[240:243], v253 offset:12960
	v_add_co_u32_e32 v244, vcc, 0x16030000, v244
	s_waitcnt lgkmcnt(5)
	v_mfma_f32_32x32x16_bf16 v[66:81], v[220:223], v[126:129], v[66:81]
	ds_read_b128 v[196:199], v253 offset:192
	s_waitcnt lgkmcnt(5)
	v_mfma_f32_32x32x16_bf16 v[82:97], v[224:227], v[126:129], v[82:97]
	ds_read_b128 v[200:203], v253 offset:12992
	s_nop 1
	s_waitcnt lgkmcnt(5)
	v_mfma_f32_32x32x16_bf16 v[66:81], v[228:231], v[130:133], v[66:81]
	ds_read_b128 v[204:207], v253 offset:224
	v_addc_co_u32_e32 v245, vcc, 0, v245, vcc
	s_waitcnt lgkmcnt(5)
	v_mfma_f32_32x32x16_bf16 v[82:97], v[232:235], v[130:133], v[82:97]
	ds_read_b128 v[208:211], v253 offset:13024
	global_load_dwordx4 v[98:101], v[246:247], off
	s_waitcnt lgkmcnt(5)
	v_mfma_f32_32x32x16_bf16 v[66:81], v[236:239], v[134:137], v[66:81]
	ds_read_b128 v[212:215], v253 offset:256
	global_load_dwordx4 v[102:105], v[244:245], off
	s_waitcnt lgkmcnt(5)
	v_mfma_f32_32x32x16_bf16 v[82:97], v[240:243], v[134:137], v[82:97]
	ds_read_b128 v[216:219], v253 offset:13056
	v_lshl_add_u64 v[246:247], s[2:3], 0, v[178:179]
	s_waitcnt lgkmcnt(5)
	v_mfma_f32_32x32x16_bf16 v[66:81], v[196:199], v[138:141], v[66:81]
	ds_read_b128 v[220:223], v253 offset:288
	s_waitcnt lgkmcnt(5)
	v_mfma_f32_32x32x16_bf16 v[82:97], v[200:203], v[138:141], v[82:97]
	ds_read_b128 v[224:227], v253 offset:13088
	v_add_co_u32_e32 v248, vcc, 0x1a000000, v246
	s_waitcnt lgkmcnt(5)
	v_mfma_f32_32x32x16_bf16 v[66:81], v[204:207], v[142:145], v[66:81]
	ds_read_b128 v[228:231], v253 offset:320
	v_lshl_add_u64 v[244:245], s[2:3], 0, v[174:175]
	s_waitcnt lgkmcnt(5)
	v_mfma_f32_32x32x16_bf16 v[82:97], v[208:211], v[142:145], v[82:97]
	ds_read_b128 v[232:235], v253 offset:13120
	s_nop 0
	s_waitcnt lgkmcnt(5)
	v_mfma_f32_32x32x16_bf16 v[66:81], v[212:215], v[150:153], v[66:81]
	ds_read_b128 v[236:239], v253 offset:352
	v_addc_co_u32_e32 v249, vcc, 0, v247, vcc
	s_waitcnt lgkmcnt(5)
	v_mfma_f32_32x32x16_bf16 v[82:97], v[216:219], v[150:153], v[82:97]
	ds_read_b128 v[240:243], v253 offset:13152
	global_load_dwordx4 v[106:109], v[244:245], off
	s_waitcnt lgkmcnt(5)
	v_mfma_f32_32x32x16_bf16 v[66:81], v[220:223], v[154:157], v[66:81]
	s_waitcnt lgkmcnt(4)
	v_mfma_f32_32x32x16_bf16 v[82:97], v[224:227], v[154:157], v[82:97]
	global_load_dwordx4 v[114:117], v[248:249], off offset:128
	s_waitcnt lgkmcnt(3)
	v_mfma_f32_32x32x16_bf16 v[66:81], v[228:231], v[158:161], v[66:81]
	v_add_co_u32_e32 v244, vcc, 0x1a400000, v246
	s_waitcnt lgkmcnt(2)
	v_mfma_f32_32x32x16_bf16 v[82:97], v[232:235], v[158:161], v[82:97]
	s_nop 1
	s_waitcnt lgkmcnt(1)
	v_mfma_f32_32x32x16_bf16 v[66:81], v[236:239], v[162:165], v[66:81]
	v_addc_co_u32_e32 v245, vcc, 0, v247, vcc
	s_waitcnt lgkmcnt(0)
	v_mfma_f32_32x32x16_bf16 v[82:97], v[240:243], v[162:165], v[82:97]
	global_load_dwordx4 v[146:149], v[244:245], off offset:128
	ds_read_b128 v[196:199], v252 offset:25600
	ds_read_b128 v[200:203], v252 offset:30208
	ds_read_b128 v[204:207], v252 offset:34816
	ds_read_b128 v[208:211], v252 offset:39424
	ds_read_b128 v[212:215], v252 offset:25632
	ds_read_b128 v[216:219], v252 offset:30240
	s_setprio 0
	s_add_i32 s54, s52, 63
	s_cmp_le_i32 s54, s47
	s_cbranch_scc1 .LaF1_1
	v_add_u32_e32 v0, s52, v168
	v_add_u32_e32 v184, 32, v0
	v_cmp_le_i32_e32 vcc, v184, v173
	v_add_u32_e32 v184, 33, v0
	s_nop 3
	v_cndmask_b32_e32 v82, v180, v82, vcc
	v_cmp_lt_i32_e32 vcc, v0, v173
	s_nop 1
	v_cndmask_b32_e32 v67, v180, v67, vcc
	v_cmp_le_i32_e32 vcc, v0, v173
	s_nop 1
	v_cndmask_b32_e32 v66, v180, v66, vcc
	v_cmp_le_i32_e32 vcc, v184, v173
	v_add_u32_e32 v184, 2, v0
	s_nop 0
	v_cndmask_b32_e32 v83, v180, v83, vcc
	v_cmp_le_i32_e32 vcc, v184, v173
	v_add_u32_e32 v184, 34, v0
	s_nop 0
	v_cndmask_b32_e32 v68, v180, v68, vcc
	v_cmp_le_i32_e32 vcc, v184, v173
	v_add_u32_e32 v184, 3, v0
	s_nop 0
	v_cndmask_b32_e32 v84, v180, v84, vcc
	v_cmp_le_i32_e32 vcc, v184, v173
	v_add_u32_e32 v184, 35, v0
	s_nop 0
	v_cndmask_b32_e32 v69, v180, v69, vcc
	v_cmp_le_i32_e32 vcc, v184, v173
	v_add_u32_e32 v184, 4, v0
	s_nop 0
	v_cndmask_b32_e32 v85, v180, v85, vcc
	v_cmp_le_i32_e32 vcc, v184, v173
	v_add_u32_e32 v184, 36, v0
	s_nop 0
	v_cndmask_b32_e32 v70, v180, v70, vcc
	v_cmp_le_i32_e32 vcc, v184, v173
	v_add_u32_e32 v184, 5, v0
	s_nop 0
	v_cndmask_b32_e32 v86, v180, v86, vcc
	v_cmp_le_i32_e32 vcc, v184, v173
	v_add_u32_e32 v184, 37, v0
	s_nop 0
	v_cndmask_b32_e32 v71, v180, v71, vcc
	v_cmp_le_i32_e32 vcc, v184, v173
	v_add_u32_e32 v184, 6, v0
	s_nop 0
	v_cndmask_b32_e32 v87, v180, v87, vcc
	v_cmp_le_i32_e32 vcc, v184, v173
	v_add_u32_e32 v184, 38, v0
	s_nop 0
	v_cndmask_b32_e32 v72, v180, v72, vcc
	v_cmp_le_i32_e32 vcc, v184, v173
	v_add_u32_e32 v184, 7, v0
	s_nop 0
	v_cndmask_b32_e32 v88, v180, v88, vcc
	v_cmp_le_i32_e32 vcc, v184, v173
	v_add_u32_e32 v184, 39, v0
	s_nop 0
	v_cndmask_b32_e32 v73, v180, v73, vcc
	v_cmp_le_i32_e32 vcc, v184, v173
	v_add_u32_e32 v184, 16, v0
	s_nop 0
	v_cndmask_b32_e32 v89, v180, v89, vcc
	v_cmp_le_i32_e32 vcc, v184, v173
	v_add_u32_e32 v184, 48, v0
	s_nop 0
	v_cndmask_b32_e32 v74, v180, v74, vcc
	v_cmp_le_i32_e32 vcc, v184, v173
	v_add_u32_e32 v184, 17, v0
	s_nop 0
	v_cndmask_b32_e32 v90, v180, v90, vcc
	v_cmp_le_i32_e32 vcc, v184, v173
	v_add_u32_e32 v184, 49, v0
	s_nop 0
	v_cndmask_b32_e32 v75, v180, v75, vcc
	v_cmp_le_i32_e32 vcc, v184, v173
	v_add_u32_e32 v184, 18, v0
	s_nop 0
	v_cndmask_b32_e32 v91, v180, v91, vcc
	v_cmp_le_i32_e32 vcc, v184, v173
	v_add_u32_e32 v184, 50, v0
	s_nop 0
	v_cndmask_b32_e32 v76, v180, v76, vcc
	v_cmp_le_i32_e32 vcc, v184, v173
	v_add_u32_e32 v184, 19, v0
	s_nop 0
	v_cndmask_b32_e32 v92, v180, v92, vcc
	v_cmp_le_i32_e32 vcc, v184, v173
	v_add_u32_e32 v184, 51, v0
	s_nop 0
	v_cndmask_b32_e32 v77, v180, v77, vcc
	v_cmp_le_i32_e32 vcc, v184, v173
	v_add_u32_e32 v184, 20, v0
	s_nop 0
	v_cndmask_b32_e32 v93, v180, v93, vcc
	v_cmp_le_i32_e32 vcc, v184, v173
	v_add_u32_e32 v184, 52, v0
	s_nop 0
	v_cndmask_b32_e32 v78, v180, v78, vcc
	v_cmp_le_i32_e32 vcc, v184, v173
	v_add_u32_e32 v184, 21, v0
	s_nop 0
	v_cndmask_b32_e32 v94, v180, v94, vcc
	v_cmp_le_i32_e32 vcc, v184, v173
	v_add_u32_e32 v184, 53, v0
	s_nop 0
	v_cndmask_b32_e32 v79, v180, v79, vcc
	v_cmp_le_i32_e32 vcc, v184, v173
	v_add_u32_e32 v184, 22, v0
	s_nop 0
	v_cndmask_b32_e32 v95, v180, v95, vcc
	v_cmp_le_i32_e32 vcc, v184, v173
	v_add_u32_e32 v184, 54, v0
	s_nop 0
	v_cndmask_b32_e32 v80, v180, v80, vcc
	v_cmp_le_i32_e32 vcc, v184, v173
	v_add_u32_e32 v184, 23, v0
	v_add_u32_e32 v0, 55, v0
	v_cndmask_b32_e32 v96, v180, v96, vcc
	v_cmp_le_i32_e32 vcc, v184, v173
	s_nop 1
	v_cndmask_b32_e32 v81, v180, v81, vcc
	v_cmp_le_i32_e32 vcc, v0, v173
	s_nop 1
	v_cndmask_b32_e32 v97, v180, v97, vcc

.LaF1_2:
	v_sub_f32_e32 v66, v66, v183
	v_sub_f32_e32 v67, v67, v183
	v_sub_f32_e32 v68, v68, v183
	v_sub_f32_e32 v69, v69, v183
	v_sub_f32_e32 v70, v70, v183
	v_sub_f32_e32 v71, v71, v183
	v_sub_f32_e32 v72, v72, v183
	v_sub_f32_e32 v73, v73, v183
	v_sub_f32_e32 v74, v74, v183
	v_sub_f32_e32 v75, v75, v183
	v_sub_f32_e32 v76, v76, v183
	v_sub_f32_e32 v77, v77, v183
	v_sub_f32_e32 v78, v78, v183
	v_sub_f32_e32 v79, v79, v183
	v_sub_f32_e32 v80, v80, v183
	v_sub_f32_e32 v81, v81, v183
	v_exp_f32_e32 v66, v66
	v_exp_f32_e32 v67, v67
	v_exp_f32_e32 v68, v68
	v_exp_f32_e32 v69, v69
	v_exp_f32_e32 v70, v70
	v_exp_f32_e32 v71, v71
	v_exp_f32_e32 v72, v72
	v_exp_f32_e32 v73, v73
	v_exp_f32_e32 v74, v74
	v_exp_f32_e32 v75, v75
	v_exp_f32_e32 v76, v76
	v_exp_f32_e32 v77, v77
	v_exp_f32_e32 v78, v78
	v_exp_f32_e32 v79, v79
	v_exp_f32_e32 v80, v80
	v_exp_f32_e32 v81, v81
	v_pk_add_f32 v[184:185], v[66:67], v[68:69]
	v_pk_add_f32 v[186:187], v[70:71], v[72:73]
	v_pk_add_f32 v[184:185], v[184:185], v[74:75]
	v_pk_add_f32 v[186:187], v[186:187], v[76:77]
	v_pk_add_f32 v[184:185], v[184:185], v[78:79]
	v_pk_add_f32 v[186:187], v[186:187], v[80:81]
	v_cvt_pk_bf16_f32 v66, v66, v67
	v_cvt_pk_bf16_f32 v67, v68, v69
	v_cvt_pk_bf16_f32 v68, v70, v71
	v_cvt_pk_bf16_f32 v69, v72, v73
	v_cvt_pk_bf16_f32 v70, v74, v75
	v_cvt_pk_bf16_f32 v71, v76, v77
	v_cvt_pk_bf16_f32 v72, v78, v79
	v_cvt_pk_bf16_f32 v73, v80, v81
	s_nop 1
	s_setprio 1
	s_waitcnt lgkmcnt(5)
	v_mfma_f32_32x32x16_bf16 v[50:65], v[196:199], v[66:69], v[50:65]
	ds_read_b128 v[220:223], v252 offset:34848
	v_sub_f32_e32 v82, v82, v183
	v_sub_f32_e32 v83, v83, v183
	v_sub_f32_e32 v84, v84, v183
	v_exp_f32_e32 v82, v82
	v_sub_f32_e32 v85, v85, v183
	v_exp_f32_e32 v83, v83
	s_waitcnt lgkmcnt(5)
	v_mfma_f32_32x32x16_bf16 v[34:49], v[200:203], v[66:69], v[34:49]
	ds_read_b128 v[224:227], v252 offset:39456
	v_sub_f32_e32 v86, v86, v183
	v_exp_f32_e32 v84, v84
	v_sub_f32_e32 v87, v87, v183
	v_exp_f32_e32 v85, v85
	v_sub_f32_e32 v88, v88, v183
	v_exp_f32_e32 v86, v86
	s_waitcnt lgkmcnt(5)
	v_mfma_f32_32x32x16_bf16 v[18:33], v[204:207], v[66:69], v[18:33]
	ds_read_b128 v[228:231], v252 offset:25664
	v_sub_f32_e32 v89, v89, v183
	v_exp_f32_e32 v87, v87
	v_sub_f32_e32 v90, v90, v183
	v_exp_f32_e32 v88, v88
	v_sub_f32_e32 v91, v91, v183
	s_waitcnt lgkmcnt(5)
	v_mfma_f32_32x32x16_bf16 v[2:17], v[208:211], v[66:69], v[2:17]
	ds_read_b128 v[232:235], v252 offset:30272
	v_exp_f32_e32 v89, v89
	v_sub_f32_e32 v92, v92, v183
	v_exp_f32_e32 v90, v90
	v_sub_f32_e32 v93, v93, v183
	v_exp_f32_e32 v91, v91
	v_sub_f32_e32 v94, v94, v183
	s_waitcnt lgkmcnt(5)
	v_mfma_f32_32x32x16_bf16 v[50:65], v[212:215], v[70:73], v[50:65]
	ds_read_b128 v[236:239], v252 offset:34880
	v_exp_f32_e32 v92, v92
	v_sub_f32_e32 v95, v95, v183
	v_exp_f32_e32 v93, v93
	v_sub_f32_e32 v96, v96, v183
	v_exp_f32_e32 v94, v94
	v_sub_f32_e32 v97, v97, v183
	s_waitcnt lgkmcnt(5)
	v_mfma_f32_32x32x16_bf16 v[34:49], v[216:219], v[70:73], v[34:49]
	ds_read_b128 v[240:243], v252 offset:39488
	v_exp_f32_e32 v95, v95
	v_exp_f32_e32 v96, v96
	v_exp_f32_e32 v97, v97
	v_pk_add_f32 v[184:185], v[184:185], v[82:83]
	v_pk_add_f32 v[186:187], v[186:187], v[84:85]
	v_pk_add_f32 v[184:185], v[184:185], v[86:87]
	s_waitcnt lgkmcnt(5)
	v_mfma_f32_32x32x16_bf16 v[18:33], v[220:223], v[70:73], v[18:33]
	ds_read_b128 v[196:199], v252 offset:25696
	v_pk_add_f32 v[186:187], v[186:187], v[88:89]
	v_pk_add_f32 v[184:185], v[184:185], v[90:91]
	v_pk_add_f32 v[186:187], v[186:187], v[92:93]
	v_pk_add_f32 v[184:185], v[184:185], v[94:95]
	v_pk_add_f32 v[186:187], v[186:187], v[96:97]
	v_pk_add_f32 v[184:185], v[184:185], v[186:187]
	v_cvt_pk_bf16_f32 v74, v82, v83
	v_cvt_pk_bf16_f32 v75, v84, v85
	s_waitcnt lgkmcnt(5)
	v_mfma_f32_32x32x16_bf16 v[2:17], v[224:227], v[70:73], v[2:17]
	ds_read_b128 v[200:203], v252 offset:30304
	v_cvt_pk_bf16_f32 v76, v86, v87
	v_cvt_pk_bf16_f32 v77, v88, v89
	v_cvt_pk_bf16_f32 v78, v90, v91
	v_cvt_pk_bf16_f32 v79, v92, v93
	v_cvt_pk_bf16_f32 v80, v94, v95
	v_cvt_pk_bf16_f32 v81, v96, v97
	v_add_f32_e32 v184, v184, v185
	v_add_f32_e32 v182, v182, v184
	s_waitcnt lgkmcnt(5)
	v_mfma_f32_32x32x16_bf16 v[50:65], v[228:231], v[74:77], v[50:65]
	ds_read_b128 v[204:207], v252 offset:34912
	s_bitcmp1_b32 s51, 0
	s_cselect_b32 s99, 0xac00, 0
	s_waitcnt lgkmcnt(5)
	v_mfma_f32_32x32x16_bf16 v[34:49], v[232:235], v[74:77], v[34:49]
	ds_read_b128 v[208:211], v252 offset:39520
	s_add_i32 s99, s99, 0
	v_add_u32_e32 v250, s99, v170
	s_waitcnt lgkmcnt(5)
	v_mfma_f32_32x32x16_bf16 v[18:33], v[236:239], v[74:77], v[18:33]
	s_waitcnt vmcnt(4)
	ds_write_b128 v250, v[98:101]
	s_waitcnt lgkmcnt(5)
	v_mfma_f32_32x32x16_bf16 v[2:17], v[240:243], v[74:77], v[2:17]
	s_waitcnt vmcnt(3)
	ds_write_b128 v250, v[102:105] offset:12800
	s_waitcnt lgkmcnt(5)
	v_mfma_f32_32x32x16_bf16 v[50:65], v[196:199], v[78:81], v[50:65]
	v_add_u32_e32 v250, s99, v172
	s_waitcnt vmcnt(2)
	s_waitcnt lgkmcnt(4)
	v_mfma_f32_32x32x16_bf16 v[34:49], v[200:203], v[78:81], v[34:49]
	ds_write_b128 v250, v[106:109] offset:256
	v_add_u32_e32 v250, s99, v169
	s_waitcnt lgkmcnt(4)
	v_mfma_f32_32x32x16_bf16 v[18:33], v[204:207], v[78:81], v[18:33]
	s_waitcnt vmcnt(1)
	ds_write_b128 v250, v[114:117] offset:25600
	s_waitcnt lgkmcnt(4)
	v_mfma_f32_32x32x16_bf16 v[2:17], v[208:211], v[78:81], v[2:17]
	s_waitcnt vmcnt(0)
	ds_write_b128 v250, v[146:149] offset:34816
	s_setprio 0
	s_branch .LBB0_1478

.LaF2_fast:
	s_waitcnt vmcnt(0)
	s_bitcmp1_b32 s36, 0
	s_cselect_b32 s4, 0, 0xac00
	s_setprio 1
	v_add_u32_e32 v253, s4, v171
	v_add_u32_e32 v252, s4, v181
	ds_read_b128 v[196:199], v253
	ds_read_b128 v[200:203], v253 offset:12800
	ds_read_b128 v[204:207], v253 offset:32
	ds_read_b128 v[208:211], v253 offset:12832
	ds_read_b128 v[212:215], v253 offset:64
	ds_read_b128 v[216:219], v253 offset:12864
	s_waitcnt lgkmcnt(5)
	v_mfma_f32_32x32x16_bf16 v[66:81], v[196:199], v[110:113], 0
	ds_read_b128 v[220:223], v253 offset:96
	s_waitcnt lgkmcnt(5)
	v_mfma_f32_32x32x16_bf16 v[82:97], v[200:203], v[110:113], 0
	ds_read_b128 v[224:227], v253 offset:12896
	v_lshl_add_u64 v[244:245], s[2:3], 0, v[176:177]
	s_waitcnt lgkmcnt(5)
	v_mfma_f32_32x32x16_bf16 v[66:81], v[204:207], v[114:117], v[66:81]
	ds_read_b128 v[228:231], v253 offset:128
	v_add_co_u32_e32 v246, vcc, 0x16020000, v244
	s_waitcnt lgkmcnt(5)
	v_mfma_f32_32x32x16_bf16 v[82:97], v[208:211], v[114:117], v[82:97]
	ds_read_b128 v[232:235], v253 offset:12928
	s_nop 1
	s_waitcnt lgkmcnt(5)
	v_mfma_f32_32x32x16_bf16 v[66:81], v[212:215], v[118:121], v[66:81]
	ds_read_b128 v[236:239], v253 offset:160
	v_addc_co_u32_e32 v247, vcc, 0, v245, vcc
	s_waitcnt lgkmcnt(5)
	v_mfma_f32_32x32x16_bf16 v[82:97], v[216:219], v[118:121], v[82:97]
	ds_read_b128 v[240:243], v253 offset:12960
	v_add_co_u32_e32 v244, vcc, 0x16030000, v244
	s_waitcnt lgkmcnt(5)
	v_mfma_f32_32x32x16_bf16 v[66:81], v[220:223], v[122:125], v[66:81]
	ds_read_b128 v[196:199], v253 offset:192
	s_waitcnt lgkmcnt(5)
	v_mfma_f32_32x32x16_bf16 v[82:97], v[224:227], v[122:125], v[82:97]
	ds_read_b128 v[200:203], v253 offset:12992
	s_nop 1
	s_waitcnt lgkmcnt(5)
	v_mfma_f32_32x32x16_bf16 v[66:81], v[228:231], v[130:133], v[66:81]
	ds_read_b128 v[204:207], v253 offset:224
	v_addc_co_u32_e32 v245, vcc, 0, v245, vcc
	s_waitcnt lgkmcnt(5)
	v_mfma_f32_32x32x16_bf16 v[82:97], v[232:235], v[130:133], v[82:97]
	ds_read_b128 v[208:211], v253 offset:13024
	global_load_dwordx4 v[98:101], v[246:247], off
	s_waitcnt lgkmcnt(5)
	v_mfma_f32_32x32x16_bf16 v[66:81], v[236:239], v[134:137], v[66:81]
	ds_read_b128 v[212:215], v253 offset:256
	global_load_dwordx4 v[102:105], v[244:245], off
	s_waitcnt lgkmcnt(5)
	v_mfma_f32_32x32x16_bf16 v[82:97], v[240:243], v[134:137], v[82:97]
	ds_read_b128 v[216:219], v253 offset:13056
	v_lshl_add_u64 v[246:247], s[2:3], 0, v[178:179]
	s_waitcnt lgkmcnt(5)
	v_mfma_f32_32x32x16_bf16 v[66:81], v[196:199], v[138:141], v[66:81]
	ds_read_b128 v[220:223], v253 offset:288
	s_waitcnt lgkmcnt(5)
	v_mfma_f32_32x32x16_bf16 v[82:97], v[200:203], v[138:141], v[82:97]
	ds_read_b128 v[224:227], v253 offset:13088
	v_add_co_u32_e32 v248, vcc, 0x1a000000, v246
	s_waitcnt lgkmcnt(5)
	v_mfma_f32_32x32x16_bf16 v[66:81], v[204:207], v[142:145], v[66:81]
	ds_read_b128 v[228:231], v253 offset:320
	v_lshl_add_u64 v[244:245], s[2:3], 0, v[174:175]
	s_waitcnt lgkmcnt(5)
	v_mfma_f32_32x32x16_bf16 v[82:97], v[208:211], v[142:145], v[82:97]
	ds_read_b128 v[232:235], v253 offset:13120
	s_nop 0
	s_waitcnt lgkmcnt(5)
	v_mfma_f32_32x32x16_bf16 v[66:81], v[212:215], v[146:149], v[66:81]
	ds_read_b128 v[236:239], v253 offset:352
	v_addc_co_u32_e32 v249, vcc, 0, v247, vcc
	s_waitcnt lgkmcnt(5)
	v_mfma_f32_32x32x16_bf16 v[82:97], v[216:219], v[146:149], v[82:97]
	ds_read_b128 v[240:243], v253 offset:13152
	global_load_dwordx4 v[106:109], v[244:245], off
	s_waitcnt lgkmcnt(5)
	v_mfma_f32_32x32x16_bf16 v[66:81], v[220:223], v[154:157], v[66:81]
	s_waitcnt lgkmcnt(4)
	v_mfma_f32_32x32x16_bf16 v[82:97], v[224:227], v[154:157], v[82:97]
	global_load_dwordx4 v[126:129], v[248:249], off offset:128
	s_waitcnt lgkmcnt(3)
	v_mfma_f32_32x32x16_bf16 v[66:81], v[228:231], v[158:161], v[66:81]
	v_add_co_u32_e32 v244, vcc, 0x1a400000, v246
	s_waitcnt lgkmcnt(2)
	v_mfma_f32_32x32x16_bf16 v[82:97], v[232:235], v[158:161], v[82:97]
	s_nop 1
	s_waitcnt lgkmcnt(1)
	v_mfma_f32_32x32x16_bf16 v[66:81], v[236:239], v[162:165], v[66:81]
	v_addc_co_u32_e32 v245, vcc, 0, v247, vcc
	s_waitcnt lgkmcnt(0)
	v_mfma_f32_32x32x16_bf16 v[82:97], v[240:243], v[162:165], v[82:97]
	global_load_dwordx4 v[150:153], v[244:245], off offset:128
	ds_read_b128 v[196:199], v252 offset:25600
	ds_read_b128 v[200:203], v252 offset:30208
	ds_read_b128 v[204:207], v252 offset:34816
	ds_read_b128 v[208:211], v252 offset:39424
	ds_read_b128 v[212:215], v252 offset:25632
	ds_read_b128 v[216:219], v252 offset:30240
	s_setprio 0
	s_add_i32 s26, s37, 63
	s_cmp_le_i32 s26, s30
	s_cbranch_scc1 .LaF2_1
	v_add_u32_e32 v0, s37, v168
	v_add_u32_e32 v184, 32, v0
	v_cmp_le_i32_e32 vcc, v184, v173
	v_add_u32_e32 v184, 33, v0
	s_nop 3
	v_cndmask_b32_e32 v82, v180, v82, vcc
	v_cmp_lt_i32_e32 vcc, v0, v173
	s_nop 1
	v_cndmask_b32_e32 v67, v180, v67, vcc
	v_cmp_le_i32_e32 vcc, v0, v173
	s_nop 1
	v_cndmask_b32_e32 v66, v180, v66, vcc
	v_cmp_le_i32_e32 vcc, v184, v173
	v_add_u32_e32 v184, 2, v0
	s_nop 0
	v_cndmask_b32_e32 v83, v180, v83, vcc
	v_cmp_le_i32_e32 vcc, v184, v173
	v_add_u32_e32 v184, 34, v0
	s_nop 0
	v_cndmask_b32_e32 v68, v180, v68, vcc
	v_cmp_le_i32_e32 vcc, v184, v173
	v_add_u32_e32 v184, 3, v0
	s_nop 0
	v_cndmask_b32_e32 v84, v180, v84, vcc
	v_cmp_le_i32_e32 vcc, v184, v173
	v_add_u32_e32 v184, 35, v0
	s_nop 0
	v_cndmask_b32_e32 v69, v180, v69, vcc
	v_cmp_le_i32_e32 vcc, v184, v173
	v_add_u32_e32 v184, 4, v0
	s_nop 0
	v_cndmask_b32_e32 v85, v180, v85, vcc
	v_cmp_le_i32_e32 vcc, v184, v173
	v_add_u32_e32 v184, 36, v0
	s_nop 0
	v_cndmask_b32_e32 v70, v180, v70, vcc
	v_cmp_le_i32_e32 vcc, v184, v173
	v_add_u32_e32 v184, 5, v0
	s_nop 0
	v_cndmask_b32_e32 v86, v180, v86, vcc
	v_cmp_le_i32_e32 vcc, v184, v173
	v_add_u32_e32 v184, 37, v0
	s_nop 0
	v_cndmask_b32_e32 v71, v180, v71, vcc
	v_cmp_le_i32_e32 vcc, v184, v173
	v_add_u32_e32 v184, 6, v0
	s_nop 0
	v_cndmask_b32_e32 v87, v180, v87, vcc
	v_cmp_le_i32_e32 vcc, v184, v173
	v_add_u32_e32 v184, 38, v0
	s_nop 0
	v_cndmask_b32_e32 v72, v180, v72, vcc
	v_cmp_le_i32_e32 vcc, v184, v173
	v_add_u32_e32 v184, 7, v0
	s_nop 0
	v_cndmask_b32_e32 v88, v180, v88, vcc
	v_cmp_le_i32_e32 vcc, v184, v173
	v_add_u32_e32 v184, 39, v0
	s_nop 0
	v_cndmask_b32_e32 v73, v180, v73, vcc
	v_cmp_le_i32_e32 vcc, v184, v173
	v_add_u32_e32 v184, 16, v0
	s_nop 0
	v_cndmask_b32_e32 v89, v180, v89, vcc
	v_cmp_le_i32_e32 vcc, v184, v173
	v_add_u32_e32 v184, 48, v0
	s_nop 0
	v_cndmask_b32_e32 v74, v180, v74, vcc
	v_cmp_le_i32_e32 vcc, v184, v173
	v_add_u32_e32 v184, 17, v0
	s_nop 0
	v_cndmask_b32_e32 v90, v180, v90, vcc
	v_cmp_le_i32_e32 vcc, v184, v173
	v_add_u32_e32 v184, 49, v0
	s_nop 0
	v_cndmask_b32_e32 v75, v180, v75, vcc
	v_cmp_le_i32_e32 vcc, v184, v173
	v_add_u32_e32 v184, 18, v0
	s_nop 0
	v_cndmask_b32_e32 v91, v180, v91, vcc
	v_cmp_le_i32_e32 vcc, v184, v173
	v_add_u32_e32 v184, 50, v0
	s_nop 0
	v_cndmask_b32_e32 v76, v180, v76, vcc
	v_cmp_le_i32_e32 vcc, v184, v173
	v_add_u32_e32 v184, 19, v0
	s_nop 0
	v_cndmask_b32_e32 v92, v180, v92, vcc
	v_cmp_le_i32_e32 vcc, v184, v173
	v_add_u32_e32 v184, 51, v0
	s_nop 0
	v_cndmask_b32_e32 v77, v180, v77, vcc
	v_cmp_le_i32_e32 vcc, v184, v173
	v_add_u32_e32 v184, 20, v0
	s_nop 0
	v_cndmask_b32_e32 v93, v180, v93, vcc
	v_cmp_le_i32_e32 vcc, v184, v173
	v_add_u32_e32 v184, 52, v0
	s_nop 0
	v_cndmask_b32_e32 v78, v180, v78, vcc
	v_cmp_le_i32_e32 vcc, v184, v173
	v_add_u32_e32 v184, 21, v0
	s_nop 0
	v_cndmask_b32_e32 v94, v180, v94, vcc
	v_cmp_le_i32_e32 vcc, v184, v173
	v_add_u32_e32 v184, 53, v0
	s_nop 0
	v_cndmask_b32_e32 v79, v180, v79, vcc
	v_cmp_le_i32_e32 vcc, v184, v173
	v_add_u32_e32 v184, 22, v0
	s_nop 0
	v_cndmask_b32_e32 v95, v180, v95, vcc
	v_cmp_le_i32_e32 vcc, v184, v173
	v_add_u32_e32 v184, 54, v0
	s_nop 0
	v_cndmask_b32_e32 v80, v180, v80, vcc
	v_cmp_le_i32_e32 vcc, v184, v173
	v_add_u32_e32 v184, 23, v0
	v_add_u32_e32 v0, 55, v0
	v_cndmask_b32_e32 v96, v180, v96, vcc
	v_cmp_le_i32_e32 vcc, v184, v173
	s_nop 1
	v_cndmask_b32_e32 v81, v180, v81, vcc
	v_cmp_le_i32_e32 vcc, v0, v173
	s_nop 1
	v_cndmask_b32_e32 v97, v180, v97, vcc

.LaF2_2:
	v_sub_f32_e32 v66, v66, v183
	v_sub_f32_e32 v67, v67, v183
	v_sub_f32_e32 v68, v68, v183
	v_sub_f32_e32 v69, v69, v183
	v_sub_f32_e32 v70, v70, v183
	v_sub_f32_e32 v71, v71, v183
	v_sub_f32_e32 v72, v72, v183
	v_sub_f32_e32 v73, v73, v183
	v_sub_f32_e32 v74, v74, v183
	v_sub_f32_e32 v75, v75, v183
	v_sub_f32_e32 v76, v76, v183
	v_sub_f32_e32 v77, v77, v183
	v_sub_f32_e32 v78, v78, v183
	v_sub_f32_e32 v79, v79, v183
	v_sub_f32_e32 v80, v80, v183
	v_sub_f32_e32 v81, v81, v183
	v_exp_f32_e32 v66, v66
	v_exp_f32_e32 v67, v67
	v_exp_f32_e32 v68, v68
	v_exp_f32_e32 v69, v69
	v_exp_f32_e32 v70, v70
	v_exp_f32_e32 v71, v71
	v_exp_f32_e32 v72, v72
	v_exp_f32_e32 v73, v73
	v_exp_f32_e32 v74, v74
	v_exp_f32_e32 v75, v75
	v_exp_f32_e32 v76, v76
	v_exp_f32_e32 v77, v77
	v_exp_f32_e32 v78, v78
	v_exp_f32_e32 v79, v79
	v_exp_f32_e32 v80, v80
	v_exp_f32_e32 v81, v81
	v_pk_add_f32 v[184:185], v[66:67], v[68:69]
	v_pk_add_f32 v[186:187], v[70:71], v[72:73]
	v_pk_add_f32 v[184:185], v[184:185], v[74:75]
	v_pk_add_f32 v[186:187], v[186:187], v[76:77]
	v_pk_add_f32 v[184:185], v[184:185], v[78:79]
	v_pk_add_f32 v[186:187], v[186:187], v[80:81]
	v_cvt_pk_bf16_f32 v66, v66, v67
	v_cvt_pk_bf16_f32 v67, v68, v69
	v_cvt_pk_bf16_f32 v68, v70, v71
	v_cvt_pk_bf16_f32 v69, v72, v73
	v_cvt_pk_bf16_f32 v70, v74, v75
	v_cvt_pk_bf16_f32 v71, v76, v77
	v_cvt_pk_bf16_f32 v72, v78, v79
	v_cvt_pk_bf16_f32 v73, v80, v81
	s_nop 1
	s_setprio 1
	s_waitcnt lgkmcnt(5)
	v_mfma_f32_32x32x16_bf16 v[50:65], v[196:199], v[66:69], v[50:65]
	ds_read_b128 v[220:223], v252 offset:34848
	v_sub_f32_e32 v82, v82, v183
	v_sub_f32_e32 v83, v83, v183
	v_sub_f32_e32 v84, v84, v183
	v_exp_f32_e32 v82, v82
	v_sub_f32_e32 v85, v85, v183
	v_exp_f32_e32 v83, v83
	s_waitcnt lgkmcnt(5)
	v_mfma_f32_32x32x16_bf16 v[34:49], v[200:203], v[66:69], v[34:49]
	ds_read_b128 v[224:227], v252 offset:39456
	v_sub_f32_e32 v86, v86, v183
	v_exp_f32_e32 v84, v84
	v_sub_f32_e32 v87, v87, v183
	v_exp_f32_e32 v85, v85
	v_sub_f32_e32 v88, v88, v183
	v_exp_f32_e32 v86, v86
	s_waitcnt lgkmcnt(5)
	v_mfma_f32_32x32x16_bf16 v[18:33], v[204:207], v[66:69], v[18:33]
	ds_read_b128 v[228:231], v252 offset:25664
	v_sub_f32_e32 v89, v89, v183
	v_exp_f32_e32 v87, v87
	v_sub_f32_e32 v90, v90, v183
	v_exp_f32_e32 v88, v88
	v_sub_f32_e32 v91, v91, v183
	s_waitcnt lgkmcnt(5)
	v_mfma_f32_32x32x16_bf16 v[2:17], v[208:211], v[66:69], v[2:17]
	ds_read_b128 v[232:235], v252 offset:30272
	v_exp_f32_e32 v89, v89
	v_sub_f32_e32 v92, v92, v183
	v_exp_f32_e32 v90, v90
	v_sub_f32_e32 v93, v93, v183
	v_exp_f32_e32 v91, v91
	v_sub_f32_e32 v94, v94, v183
	s_waitcnt lgkmcnt(5)
	v_mfma_f32_32x32x16_bf16 v[50:65], v[212:215], v[70:73], v[50:65]
	ds_read_b128 v[236:239], v252 offset:34880
	v_exp_f32_e32 v92, v92
	v_sub_f32_e32 v95, v95, v183
	v_exp_f32_e32 v93, v93
	v_sub_f32_e32 v96, v96, v183
	v_exp_f32_e32 v94, v94
	v_sub_f32_e32 v97, v97, v183
	s_waitcnt lgkmcnt(5)
	v_mfma_f32_32x32x16_bf16 v[34:49], v[216:219], v[70:73], v[34:49]
	ds_read_b128 v[240:243], v252 offset:39488
	v_exp_f32_e32 v95, v95
	v_exp_f32_e32 v96, v96
	v_exp_f32_e32 v97, v97
	v_pk_add_f32 v[184:185], v[184:185], v[82:83]
	v_pk_add_f32 v[186:187], v[186:187], v[84:85]
	v_pk_add_f32 v[184:185], v[184:185], v[86:87]
	s_waitcnt lgkmcnt(5)
	v_mfma_f32_32x32x16_bf16 v[18:33], v[220:223], v[70:73], v[18:33]
	ds_read_b128 v[196:199], v252 offset:25696
	v_pk_add_f32 v[186:187], v[186:187], v[88:89]
	v_pk_add_f32 v[184:185], v[184:185], v[90:91]
	v_pk_add_f32 v[186:187], v[186:187], v[92:93]
	v_pk_add_f32 v[184:185], v[184:185], v[94:95]
	v_pk_add_f32 v[186:187], v[186:187], v[96:97]
	v_pk_add_f32 v[184:185], v[184:185], v[186:187]
	v_cvt_pk_bf16_f32 v74, v82, v83
	v_cvt_pk_bf16_f32 v75, v84, v85
	s_waitcnt lgkmcnt(5)
	v_mfma_f32_32x32x16_bf16 v[2:17], v[224:227], v[70:73], v[2:17]
	ds_read_b128 v[200:203], v252 offset:30304
	v_cvt_pk_bf16_f32 v76, v86, v87
	v_cvt_pk_bf16_f32 v77, v88, v89
	v_cvt_pk_bf16_f32 v78, v90, v91
	v_cvt_pk_bf16_f32 v79, v92, v93
	v_cvt_pk_bf16_f32 v80, v94, v95
	v_cvt_pk_bf16_f32 v81, v96, v97
	v_add_f32_e32 v184, v184, v185
	v_add_f32_e32 v182, v182, v184
	s_waitcnt lgkmcnt(5)
	v_mfma_f32_32x32x16_bf16 v[50:65], v[228:231], v[74:77], v[50:65]
	ds_read_b128 v[204:207], v252 offset:34912
	s_bitcmp1_b32 s36, 0
	s_cselect_b32 s99, 0xac00, 0
	s_waitcnt lgkmcnt(5)
	v_mfma_f32_32x32x16_bf16 v[34:49], v[232:235], v[74:77], v[34:49]
	ds_read_b128 v[208:211], v252 offset:39520
	s_add_i32 s99, s99, 0
	v_add_u32_e32 v250, s99, v170
	s_waitcnt lgkmcnt(5)
	v_mfma_f32_32x32x16_bf16 v[18:33], v[236:239], v[74:77], v[18:33]
	s_waitcnt vmcnt(4)
	ds_write_b128 v250, v[98:101]
	s_waitcnt lgkmcnt(5)
	v_mfma_f32_32x32x16_bf16 v[2:17], v[240:243], v[74:77], v[2:17]
	s_waitcnt vmcnt(3)
	ds_write_b128 v250, v[102:105] offset:12800
	s_waitcnt lgkmcnt(5)
	v_mfma_f32_32x32x16_bf16 v[50:65], v[196:199], v[78:81], v[50:65]
	v_add_u32_e32 v250, s99, v172
	s_waitcnt vmcnt(2)
	s_waitcnt lgkmcnt(4)
	v_mfma_f32_32x32x16_bf16 v[34:49], v[200:203], v[78:81], v[34:49]
	ds_write_b128 v250, v[106:109] offset:256
	v_add_u32_e32 v250, s99, v169
	s_waitcnt lgkmcnt(4)
	v_mfma_f32_32x32x16_bf16 v[18:33], v[204:207], v[78:81], v[18:33]
	s_waitcnt vmcnt(1)
	ds_write_b128 v250, v[126:129] offset:25600
	s_waitcnt lgkmcnt(4)
	v_mfma_f32_32x32x16_bf16 v[2:17], v[208:211], v[78:81], v[2:17]
	s_waitcnt vmcnt(0)
	ds_write_b128 v250, v[150:153] offset:34816
	s_setprio 0
	s_branch .LBB0_1490
